# panel-group barrier: single arrival counter, early L1 invalidate overlapped with arrival atomic
# baseline (speedup 1.0000x reference)
.LBB0_1004:
	s_and_b64 vcc, exec, s[12:13]
	s_cbranch_vccz .LBB0_1029
	v_readlane_b32 s12, v250, 16
	v_readlane_b32 s13, v250, 17
	v_mov_b32_e32 v0, 0
	s_andn2_b64 vcc, exec, s[12:13]
	s_cbranch_vccnz .LBB0_1028
	v_mbcnt_lo_u32_b32 v0, -1, v0
	v_mbcnt_hi_u32_b32 v0, -1, v0
	v_cmp_eq_u32_e32 vcc, 0, v0
	s_and_saveexec_b64 s[12:13], vcc
	s_cbranch_execz .LBB0_1027
	v_readlane_b32 s18, v253, 8
	v_readlane_b32 s19, v253, 9
	v_mov_b32_e32 v130, 1
	s_mov_b32 s14, 0
	s_nop 2
	global_atomic_add v130, v1, v130, s[18:19] sc0
	buffer_inv sc1
	s_waitcnt vmcnt(0)
	v_and_b32_e32 v0, -4, v130
	v_add_u32_e32 v0, 4, v0
	v_add_u32_e32 v130, 1, v130
.Lxb2_spin_0:
	v_sub_u32_e32 v130, v130, v0
	v_cmp_gt_i32_e32 vcc, 0, v130
	s_cbranch_vccz .Lxb2_done_0
	s_sleep 1
	global_load_dword v130, v1, s[18:19] sc1
	s_add_i32 s14, s14, 1
	s_waitcnt vmcnt(0)
	s_cmp_lt_u32 s14, 0x100000
	s_cbranch_scc1 .Lxb2_spin_0
.Lxb2_done_0:
.LBB0_1027:
	s_or_b64 exec, exec, s[12:13]

.LBB0_1189:
	s_and_b64 vcc, exec, s[2:3]
	s_cbranch_vccz .LBB0_1214
	v_readlane_b32 s2, v250, 16
	v_readlane_b32 s3, v250, 17
	v_mov_b32_e32 v0, v1
	s_andn2_b64 vcc, exec, s[2:3]
	s_cbranch_vccnz .LBB0_1213
	v_mbcnt_lo_u32_b32 v0, -1, v0
	v_mbcnt_hi_u32_b32 v0, -1, v0
	v_cmp_eq_u32_e32 vcc, 0, v0
	s_and_saveexec_b64 s[2:3], vcc
	s_cbranch_execz .LBB0_1212
	v_readlane_b32 s6, v253, 8
	v_readlane_b32 s7, v253, 9
	v_mov_b32_e32 v2, 1
	s_mov_b32 s4, 0
	s_nop 2
	global_atomic_add v2, v1, v2, s[6:7] sc0
	buffer_inv sc1
	s_waitcnt vmcnt(0)
	v_and_b32_e32 v0, -4, v2
	v_add_u32_e32 v0, 4, v0
	v_add_u32_e32 v2, 1, v2
.Lxb2_spin_1:
	v_sub_u32_e32 v2, v2, v0
	v_cmp_gt_i32_e32 vcc, 0, v2
	s_cbranch_vccz .Lxb2_done_1
	s_sleep 1
	global_load_dword v2, v1, s[6:7] sc1
	s_add_i32 s4, s4, 1
	s_waitcnt vmcnt(0)
	s_cmp_lt_u32 s4, 0x100000
	s_cbranch_scc1 .Lxb2_spin_1
.Lxb2_done_1:
.LBB0_1212:
	s_or_b64 exec, exec, s[2:3]

.LBB0_1311:
	s_and_b64 vcc, exec, s[0:1]
	s_cbranch_vccz .LBB0_1336
	v_readlane_b32 s0, v250, 16
	v_readlane_b32 s1, v250, 17
	v_mov_b32_e32 v0, v1
	s_andn2_b64 vcc, exec, s[0:1]
	s_cbranch_vccnz .LBB0_1335
	v_mbcnt_lo_u32_b32 v0, -1, v0
	v_mbcnt_hi_u32_b32 v0, -1, v0
	v_cmp_eq_u32_e32 vcc, 0, v0
	s_and_saveexec_b64 s[0:1], vcc
	s_cbranch_execz .LBB0_1334
	v_readlane_b32 s4, v253, 8
	v_readlane_b32 s5, v253, 9
	v_mov_b32_e32 v2, 1
	s_mov_b32 s2, 0
	s_nop 2
	global_atomic_add v2, v1, v2, s[4:5] sc0
	buffer_inv sc1
	s_waitcnt vmcnt(0)
	v_and_b32_e32 v0, -4, v2
	v_add_u32_e32 v0, 4, v0
	v_add_u32_e32 v2, 1, v2
.Lxb2_spin_2:
	v_sub_u32_e32 v2, v2, v0
	v_cmp_gt_i32_e32 vcc, 0, v2
	s_cbranch_vccz .Lxb2_done_2
	s_sleep 1
	global_load_dword v2, v1, s[4:5] sc1
	s_add_i32 s2, s2, 1
	s_waitcnt vmcnt(0)
	s_cmp_lt_u32 s2, 0x100000
	s_cbranch_scc1 .Lxb2_spin_2
.Lxb2_done_2:
.LBB0_1334:
	s_or_b64 exec, exec, s[0:1]

.LBB0_1685:
	s_and_b64 vcc, exec, s[2:3]
	s_cbranch_vccz .LBB0_1710
	v_readlane_b32 s2, v250, 16
	v_readlane_b32 s3, v250, 17
	v_mov_b32_e32 v2, v1
	s_andn2_b64 vcc, exec, s[2:3]
	s_cbranch_vccnz .LBB0_1709
	v_mbcnt_lo_u32_b32 v2, -1, v2
	v_mbcnt_hi_u32_b32 v2, -1, v2
	v_cmp_eq_u32_e32 vcc, 0, v2
	s_and_saveexec_b64 s[2:3], vcc
	s_cbranch_execz .LBB0_1708
	v_readlane_b32 s10, v253, 8
	v_readlane_b32 s11, v253, 9
	v_mov_b32_e32 v3, 1
	s_mov_b32 s8, 0
	s_nop 2
	global_atomic_add v3, v1, v3, s[10:11] sc0
	buffer_inv sc1
	s_waitcnt vmcnt(0)
	v_and_b32_e32 v2, -4, v3
	v_add_u32_e32 v2, 4, v2
	v_add_u32_e32 v3, 1, v3
.Lxb2_spin_4:
	v_sub_u32_e32 v3, v3, v2
	v_cmp_gt_i32_e32 vcc, 0, v3
	s_cbranch_vccz .Lxb2_done_4
	s_sleep 1
	global_load_dword v3, v1, s[10:11] sc1
	s_add_i32 s8, s8, 1
	s_waitcnt vmcnt(0)
	s_cmp_lt_u32 s8, 0x100000
	s_cbranch_scc1 .Lxb2_spin_4
